# norm/final phases: weight+modulation loads issued with the row loads (one round trip per row), final_norm_w hoisted out of the loop; adaLN silu staging loads batched
# speedup vs baseline: 1.0384x; 1.0068x over previous
; __device__ __forceinline__ int launder(int x) { asm volatile("" : "+v"(x)); return x; }
; __device__ __forceinline__ void phase_final(const Params& p) {
;   const int tid = launder(threadIdx.x), lane = tid & 63, w = tid >> 6;
;   for (int t = blockIdx.x; t < 16384 / 4; t += gridDim.x) {
;     int r = t * 4 + w;
;     float* src = p.out + (size_t)r * 1024;
;     float4 v[4];
;     float ss = 0;
; #pragma unroll
;     for (int i = 0; i < 4; ++i) {
;       v[i] = *(const float4*)(src + lane * 4 + 256 * i);
;       ss += v[i].x * v[i].x + v[i].y * v[i].y + v[i].z * v[i].z + v[i].w * v[i].w;
;     }
;     ss = sum64(ss);
;     float rstd = rsqrtf(ss * (1.f / 1024.f) + 1e-6f);
; #pragma unroll
;     for (int i = 0; i < 4; ++i) {
;       int k = lane * 4 + 256 * i;
;       float4 n4 = *(const float4*)(p.final_norm_w + k);
;       float4 o;
;       o.x = v[i].x * rstd * n4.x; o.y = v[i].y * rstd * n4.y; o.z = v[i].z * rstd * n4.z; o.w = v[i].w * rstd * n4.w;
;       *(float4*)(src + k) = o;
;     }
;   }
.LBB0_73:
	v_readlane_b32 s0, v255, 39
	s_mov_b64 s[46:47], -1
	s_mov_b64 s[42:43], 0
	s_cmp_lt_i32 s0, 15
	s_mov_b64 s[44:45], 0
	s_cbranch_scc1 .LBB0_87
	v_readlane_b32 s0, v255, 39
	s_cmp_eq_u32 s0, 15
	s_mov_b64 s[44:45], -1
	s_cbranch_scc0 .LBB0_79
	v_readlane_b32 s0, v253, 6
	v_readlane_b32 s1, v253, 7
	v_mov_b32_e32 v0, v189
	s_andn2_b64 vcc, exec, s[0:1]
	s_mov_b32 s46, 0x800000
	s_cbranch_vccnz .LBB0_78
	v_cmp_lt_i32_e32 vcc, v194, v193
	v_readlane_b32 s0, v252, 18
	v_readlane_b32 s1, v252, 19
	v_cndmask_b32_e32 v1, v192, v194, vcc
	v_cmp_lt_i32_e32 vcc, v195, v193
	v_lshlrev_b32_e32 v6, 2, v1
	s_load_dword s28, s[0:1], 0x0
	v_cndmask_b32_e32 v1, v192, v195, vcc
	v_cmp_lt_i32_e32 vcc, v196, v193
	v_lshlrev_b32_e32 v7, 2, v1
	v_ashrrev_i32_e32 v4, 6, v0
	v_cndmask_b32_e32 v1, v192, v196, vcc
	v_cmp_lt_i32_e32 vcc, v197, v193
	v_lshlrev_b32_e32 v8, 2, v1
	v_lshlrev_b32_e32 v0, 4, v0
	v_cndmask_b32_e32 v1, v192, v197, vcc
	v_cmp_lt_i32_e32 vcc, v198, v193
	v_lshlrev_b32_e32 v9, 2, v1
	v_readlane_b32 s0, v251, 32
	v_cndmask_b32_e32 v1, v192, v198, vcc
	v_cmp_lt_i32_e32 vcc, v199, v193
	v_lshlrev_b32_e32 v10, 2, v1
	v_and_b32_e32 v2, 0x3f0, v0
	v_cndmask_b32_e32 v1, v192, v199, vcc
	v_mov_b32_e32 v3, v164
	v_readlane_b32 s4, v251, 36
	v_readlane_b32 s5, v251, 37
	v_readlane_b32 s6, v251, 38
	v_readlane_b32 s7, v251, 39
	v_readlane_b32 s0, v254, 51
	v_lshlrev_b32_e32 v11, 2, v1
	v_lshl_add_u64 v[0:1], s[4:5], 0, v[2:3]
	v_lshl_add_u64 v[2:3], s[6:7], 0, v[2:3]
	v_add_u32_e32 v4, s0, v4
	s_waitcnt lgkmcnt(0)
	s_lshl_b32 s44, s28, 2
	s_mov_b32 s45, s93
	v_readlane_b32 s1, v251, 33
	v_readlane_b32 s2, v251, 34
	v_readlane_b32 s3, v251, 35
	v_readlane_b32 s8, v251, 40
	v_readlane_b32 s9, v251, 41
	v_readlane_b32 s10, v251, 42
	v_readlane_b32 s11, v251, 43
	v_readlane_b32 s12, v251, 44
	v_readlane_b32 s13, v251, 45
	v_readlane_b32 s14, v251, 46
	v_readlane_b32 s15, v251, 47
	global_load_dwordx4 v[50:53], v[0:1], off
	global_load_dwordx4 v[54:57], v[0:1], off offset:1024
	global_load_dwordx4 v[58:61], v[0:1], off offset:2048
	global_load_dwordx4 v[62:65], v[0:1], off offset:3072
.LBB0_77:
	v_ashrrev_i32_e32 v5, 31, v4
	v_lshlrev_b64 v[12:13], 12, v[4:5]
	s_waitcnt vmcnt(0)
	v_lshl_add_u64 v[32:33], v[2:3], 0, v[12:13]
	global_load_dwordx4 v[12:15], v[32:33], off
	global_load_dwordx4 v[16:19], v[32:33], off offset:1024
	global_load_dwordx4 v[20:23], v[32:33], off offset:2048
	global_load_dwordx4 v[24:27], v[32:33], off offset:3072
	s_add_i32 s45, s45, s28
	s_cmpk_gt_i32 s45, 0xfff
	v_add_u32_e32 v4, s44, v4
	s_waitcnt vmcnt(3)
	v_mov_b32_e32 v36, v13
	s_waitcnt vmcnt(2)
	v_mov_b32_e32 v37, v17
	v_mov_b32_e32 v34, v12
	v_mov_b32_e32 v35, v16
	s_waitcnt vmcnt(1)
	v_mov_b32_e32 v44, v21
	s_waitcnt vmcnt(0)
	v_mov_b32_e32 v45, v25
	v_pk_mul_f32 v[36:37], v[36:37], v[36:37]
	v_mov_b32_e32 v38, v14
	v_mov_b32_e32 v39, v18
	v_mov_b32_e32 v42, v20
	v_mov_b32_e32 v43, v24
	v_pk_mul_f32 v[44:45], v[44:45], v[44:45]
	v_pk_fma_f32 v[34:35], v[34:35], v[34:35], v[36:37]
	v_mov_b32_e32 v40, v15
	v_mov_b32_e32 v41, v19
	v_mov_b32_e32 v46, v22
	v_mov_b32_e32 v47, v26
	v_pk_fma_f32 v[36:37], v[42:43], v[42:43], v[44:45]
	v_pk_fma_f32 v[34:35], v[38:39], v[38:39], v[34:35]
	v_mov_b32_e32 v48, v23
	v_mov_b32_e32 v49, v27
	v_pk_fma_f32 v[36:37], v[46:47], v[46:47], v[36:37]
	v_pk_fma_f32 v[34:35], v[40:41], v[40:41], v[34:35]
	v_pk_fma_f32 v[36:37], v[48:49], v[48:49], v[36:37]
	v_add_f32_e32 v5, v34, v35
	v_add_f32_e32 v5, v5, v36
	v_add_f32_e32 v5, v5, v37
	ds_bpermute_b32 v34, v6, v5
	s_waitcnt lgkmcnt(0)
	v_add_f32_e32 v5, v5, v34
	ds_bpermute_b32 v34, v7, v5
	s_waitcnt lgkmcnt(0)
	v_add_f32_e32 v5, v5, v34
	ds_bpermute_b32 v34, v8, v5
	s_waitcnt lgkmcnt(0)
	v_add_f32_e32 v5, v5, v34
	ds_bpermute_b32 v34, v9, v5
	s_waitcnt lgkmcnt(0)
	v_add_f32_e32 v5, v5, v34
	ds_bpermute_b32 v34, v10, v5
	s_waitcnt lgkmcnt(0)
	v_add_f32_e32 v5, v5, v34
	ds_bpermute_b32 v34, v11, v5
	s_waitcnt lgkmcnt(0)
	v_add_f32_e32 v5, v5, v34
	v_fmamk_f32 v5, v5, 0x3a800000, v191
	v_mul_f32_e32 v34, 0x4b800000, v5
	v_cmp_gt_f32_e32 vcc, s46, v5
	s_nop 1
	v_cndmask_b32_e32 v5, v5, v34, vcc
	v_rsq_f32_e32 v5, v5
	s_nop 0
	v_mul_f32_e32 v34, 0x45800000, v5
	v_cndmask_b32_e32 v34, v5, v34, vcc
	v_pk_mul_f32 v[12:13], v[12:13], v[34:35] op_sel_hi:[1,0]
	v_pk_mul_f32 v[14:15], v[14:15], v[34:35] op_sel_hi:[1,0]
	s_waitcnt vmcnt(0)
	v_pk_mul_f32 v[12:13], v[50:51], v[12:13]
	v_pk_mul_f32 v[14:15], v[52:53], v[14:15]
	global_store_dwordx4 v[32:33], v[12:15], off
	s_nop 0
	v_pk_mul_f32 v[16:17], v[16:17], v[34:35] op_sel_hi:[1,0]
	v_pk_mul_f32 v[18:19], v[18:19], v[34:35] op_sel_hi:[1,0]
	v_pk_mul_f32 v[12:13], v[16:17], v[54:55]
	v_pk_mul_f32 v[14:15], v[18:19], v[56:57]
	global_store_dwordx4 v[32:33], v[12:15], off offset:1024
	s_nop 0
	v_pk_mul_f32 v[16:17], v[20:21], v[34:35] op_sel_hi:[1,0]
	v_pk_mul_f32 v[18:19], v[22:23], v[34:35] op_sel_hi:[1,0]
	v_pk_mul_f32 v[12:13], v[16:17], v[58:59]
	v_pk_mul_f32 v[14:15], v[18:19], v[60:61]
	global_store_dwordx4 v[32:33], v[12:15], off offset:2048
	s_nop 0
	v_pk_mul_f32 v[16:17], v[24:25], v[34:35] op_sel_hi:[1,0]
	v_pk_mul_f32 v[18:19], v[26:27], v[34:35] op_sel_hi:[1,0]
	v_pk_mul_f32 v[12:13], v[16:17], v[62:63]
	v_pk_mul_f32 v[14:15], v[18:19], v[64:65]
	global_store_dwordx4 v[32:33], v[12:15], off offset:3072
	s_cbranch_scc0 .LBB0_77

; __device__ __forceinline__ void phase_norm(const Params& p, int l) {
;     ...
; #pragma unroll
;     for (int i = 0; i < 4; ++i) {
;       int k = lane * 4 + 256 * i;
;       float4 n4 = *(const float4*)(nw + k), sc = *(const float4*)(md + 1024 + k), sh = *(const float4*)(md + k);
;       float h0 = v[i].x * rstd * n4.x * (1.f + sc.x) + sh.x;
;       float h1 = v[i].y * rstd * n4.y * (1.f + sc.y) + sh.y;
;       float h2 = v[i].z * rstd * n4.z * (1.f + sc.z) + sh.z;
;       float h3 = v[i].w * rstd * n4.w * (1.f + sc.w) + sh.w;
;       uint2 o;
;       o.x = pack2(h0, h1);
;       o.y = pack2(h2, h3);
;       *(uint2*)(p.hbuf + (size_t)r * 1024 + k) = o;
;     }
.LBB0_1312:
	s_or_b64 exec, exec, s[46:47]
	v_readlane_b32 s0, v251, 48
	v_readlane_b32 s2, v251, 50
	v_readlane_b32 s3, v251, 51
	v_readlane_b32 s1, v251, 49
	v_pk_mul_f32 v[12:13], v[12:13], v[32:33] op_sel_hi:[1,0]
	v_pk_mul_f32 v[14:15], v[14:15], v[32:33] op_sel_hi:[1,0]
	v_lshlrev_b64 v[34:35], 11, v[22:23]
	v_lshl_add_u64 v[34:35], v[20:21], 0, v[34:35]
	v_mov_b32_e32 v25, v164
	v_pk_mul_f32 v[8:9], v[8:9], v[32:33] op_sel_hi:[1,0]
	v_pk_mul_f32 v[10:11], v[10:11], v[32:33] op_sel_hi:[1,0]
	v_mov_b32_e32 v27, v164
	v_pk_mul_f32 v[4:5], v[4:5], v[32:33] op_sel_hi:[1,0]
	v_pk_mul_f32 v[6:7], v[6:7], v[32:33] op_sel_hi:[1,0]
	v_mov_b32_e32 v29, v164
	v_pk_mul_f32 v[0:1], v[0:1], v[32:33] op_sel_hi:[1,0]
	v_pk_mul_f32 v[2:3], v[2:3], v[32:33] op_sel_hi:[1,0]
	s_add_i32 s54, s54, s52
	s_cmpk_gt_i32 s54, 0x10ff
	v_add_u32_e32 v22, s53, v22
	v_readlane_b32 s4, v251, 52
	v_readlane_b32 s5, v251, 53
	v_readlane_b32 s6, v251, 54
	v_readlane_b32 s7, v251, 55
	v_readlane_b32 s8, v251, 56
	v_readlane_b32 s9, v251, 57
	v_readlane_b32 s10, v251, 58
	v_readlane_b32 s11, v251, 59
	v_readlane_b32 s12, v251, 60
	v_readlane_b32 s13, v251, 61
	v_readlane_b32 s14, v251, 62
	v_readlane_b32 s15, v251, 63
	s_waitcnt vmcnt(0)
	v_pk_mul_f32 v[12:13], v[12:13], v[92:93]
	v_pk_mul_f32 v[14:15], v[14:15], v[94:95]
	v_pk_add_f32 v[92:93], v[96:97], 1.0 op_sel_hi:[1,0]
	v_pk_add_f32 v[94:95], v[98:99], 1.0 op_sel_hi:[1,0]
	v_pk_fma_f32 v[12:13], v[12:13], v[92:93], v[100:101]
	v_pk_fma_f32 v[14:15], v[14:15], v[94:95], v[102:103]
	v_cvt_pk_bf16_f32 v12, v12, v13
	v_cvt_pk_bf16_f32 v13, v14, v15
	global_store_dwordx2 v[34:35], v[12:13], off
	v_pk_mul_f32 v[8:9], v[8:9], v[56:57]
	v_pk_mul_f32 v[10:11], v[10:11], v[58:59]
	v_pk_add_f32 v[56:57], v[68:69], 1.0 op_sel_hi:[1,0]
	v_pk_add_f32 v[58:59], v[70:71], 1.0 op_sel_hi:[1,0]
	v_pk_fma_f32 v[8:9], v[8:9], v[56:57], v[80:81]
	v_pk_fma_f32 v[10:11], v[10:11], v[58:59], v[82:83]
	v_cvt_pk_bf16_f32 v8, v8, v9
	v_cvt_pk_bf16_f32 v9, v10, v11
	global_store_dwordx2 v[34:35], v[8:9], off offset:512
	v_pk_mul_f32 v[4:5], v[4:5], v[60:61]
	v_pk_mul_f32 v[6:7], v[6:7], v[62:63]
	v_pk_add_f32 v[60:61], v[72:73], 1.0 op_sel_hi:[1,0]
	v_pk_add_f32 v[62:63], v[74:75], 1.0 op_sel_hi:[1,0]
	v_pk_fma_f32 v[4:5], v[4:5], v[60:61], v[84:85]
	v_pk_fma_f32 v[6:7], v[6:7], v[62:63], v[86:87]
	v_cvt_pk_bf16_f32 v4, v4, v5
	v_cvt_pk_bf16_f32 v5, v6, v7
	global_store_dwordx2 v[34:35], v[4:5], off offset:1024
	v_pk_mul_f32 v[0:1], v[0:1], v[64:65]
	v_pk_mul_f32 v[2:3], v[2:3], v[66:67]
	v_pk_add_f32 v[64:65], v[76:77], 1.0 op_sel_hi:[1,0]
	v_pk_add_f32 v[66:67], v[78:79], 1.0 op_sel_hi:[1,0]
	v_pk_fma_f32 v[0:1], v[0:1], v[64:65], v[88:89]
	v_pk_fma_f32 v[2:3], v[2:3], v[66:67], v[90:91]
	v_cvt_pk_bf16_f32 v0, v0, v1
	v_cvt_pk_bf16_f32 v1, v2, v3
	global_store_dwordx2 v[34:35], v[0:1], off offset:1536
	s_cbranch_scc1 .LBB0_1327

; __device__ __forceinline__ void phase_norm(const Params& p, int l) {
;     ...
;     if (l == 0) src = (pp < 256) ? p.ctx + ((size_t)b * 256 + pp) * 1024 : p.x + ((size_t)b * 4096 + pp - 256) * 1024;
;     else src = (pp < 256) ? p.ctxcur + ((size_t)b * 256 + pp) * 1024 : p.out + ((size_t)b * 4096 + pp - 256) * 1024;
;     const float* md = p.mod + (size_t)(l * 5 + ((pp < 256) ? 4 : b)) * 3072;
;     const float* nw = p.norm_w + l * 1024;
;     float4 v[4];
;     float ss = 0;
; #pragma unroll
;     for (int i = 0; i < 4; ++i) {
;       v[i] = *(const float4*)(src + lane * 4 + 256 * i);
;       ss += v[i].x * v[i].x + v[i].y * v[i].y + v[i].z * v[i].z + v[i].w * v[i].w;
;     }
;     ss = sum64(ss);
;     float rstd = rsqrtf(ss * (1.f / 1024.f) + 1e-6f);
;     if (lane == 0) p.rstd[r] = rstd;
; #pragma unroll
;     for (int i = 0; i < 4; ++i) {
;       int k = lane * 4 + 256 * i;
;       float4 n4 = *(const float4*)(nw + k), sc = *(const float4*)(md + 1024 + k), sh = *(const float4*)(md + k);
.LBB0_1325:
	v_lshlrev_b32_e32 v34, 2, v16
	v_mov_b32_e32 v35, v164
	v_lshl_add_u64 v[0:1], v[2:3], 0, v[34:35]
	global_load_dwordx4 v[12:15], v[0:1], off
	global_load_dwordx4 v[8:11], v[0:1], off offset:1024
	global_load_dwordx4 v[4:7], v[0:1], off offset:2048
	s_nop 0
	global_load_dwordx4 v[0:3], v[0:1], off offset:3072
	v_cndmask_b32_e64 v25, v30, 4, s[44:45]
	v_readlane_b32 s2, v251, 50
	v_readlane_b32 s3, v251, 51
	v_add_u32_e32 v25, s28, v25
	s_nop 0
	v_mov_b64_e32 v[30:31], s[2:3]
	v_mad_i64_i32 v[30:31], s[44:45], v25, s41, v[30:31]
	s_mov_b64 s[0:1], 0x1000
	v_lshl_add_u64 v[104:105], v[30:31], 0, s[0:1]
	v_lshl_add_u64 v[106:107], v[104:105], 0, v[34:35]
	v_lshl_add_u64 v[30:31], v[30:31], 0, v[34:35]
	global_load_dwordx4 v[92:95], v[18:19], off
	global_load_dwordx4 v[56:59], v[18:19], off offset:1024
	global_load_dwordx4 v[60:63], v[18:19], off offset:2048
	global_load_dwordx4 v[64:67], v[18:19], off offset:3072
	global_load_dwordx4 v[96:99], v[106:107], off
	global_load_dwordx4 v[68:71], v[106:107], off offset:1024
	global_load_dwordx4 v[72:75], v[106:107], off offset:2048
	global_load_dwordx4 v[76:79], v[106:107], off offset:3072
	global_load_dwordx4 v[100:103], v[30:31], off
	global_load_dwordx4 v[80:83], v[30:31], off offset:1024
	global_load_dwordx4 v[84:87], v[30:31], off offset:2048
	global_load_dwordx4 v[88:91], v[30:31], off offset:3072
	s_mov_b32 s0, 0x800000
	s_waitcnt vmcnt(15)
	v_mov_b32_e32 v42, v13
	s_waitcnt vmcnt(14)
	v_mov_b32_e32 v43, v9
	v_mov_b32_e32 v40, v12
	v_mov_b32_e32 v41, v8
	s_waitcnt vmcnt(13)
	v_mov_b32_e32 v50, v5
	s_waitcnt vmcnt(12)
	v_mov_b32_e32 v51, v1
	v_pk_mul_f32 v[42:43], v[42:43], v[42:43]
	v_mov_b32_e32 v44, v14
	v_mov_b32_e32 v45, v10
	v_mov_b32_e32 v48, v4
	v_mov_b32_e32 v49, v0
	v_pk_mul_f32 v[50:51], v[50:51], v[50:51]
	v_pk_fma_f32 v[40:41], v[40:41], v[40:41], v[42:43]
	v_mov_b32_e32 v46, v15
	v_mov_b32_e32 v47, v11
	v_mov_b32_e32 v52, v6
	v_mov_b32_e32 v53, v2
	v_pk_fma_f32 v[42:43], v[48:49], v[48:49], v[50:51]
	v_pk_fma_f32 v[40:41], v[44:45], v[44:45], v[40:41]
	v_mov_b32_e32 v54, v7
	v_mov_b32_e32 v55, v3
	v_pk_fma_f32 v[42:43], v[52:53], v[52:53], v[42:43]
	v_pk_fma_f32 v[40:41], v[46:47], v[46:47], v[40:41]
	v_pk_fma_f32 v[42:43], v[54:55], v[54:55], v[42:43]
	v_add_f32_e32 v23, v40, v41
	v_add_f32_e32 v23, v23, v42
	v_add_f32_e32 v23, v23, v43
	ds_bpermute_b32 v25, v17, v23
	s_waitcnt lgkmcnt(0)
	v_add_f32_e32 v23, v23, v25
	ds_bpermute_b32 v25, v33, v23
	s_waitcnt lgkmcnt(0)
	v_add_f32_e32 v23, v23, v25
	ds_bpermute_b32 v25, v36, v23
	s_waitcnt lgkmcnt(0)
	v_add_f32_e32 v23, v23, v25
	ds_bpermute_b32 v25, v37, v23
	s_waitcnt lgkmcnt(0)
	v_add_f32_e32 v23, v23, v25
	ds_bpermute_b32 v25, v38, v23
	s_waitcnt lgkmcnt(0)
	v_add_f32_e32 v23, v23, v25
	ds_bpermute_b32 v25, v39, v23
	s_waitcnt lgkmcnt(0)
	v_add_f32_e32 v23, v23, v25
	v_fmamk_f32 v23, v23, 0x3a800000, v191
	v_mul_f32_e32 v25, 0x4b800000, v23
	v_cmp_gt_f32_e32 vcc, s0, v23
	s_nop 1
	v_cndmask_b32_e32 v23, v23, v25, vcc
	v_rsq_f32_e32 v23, v23
	s_nop 0
	v_mul_f32_e32 v25, 0x45800000, v23
	v_cndmask_b32_e32 v32, v23, v25, vcc
	v_ashrrev_i32_e32 v23, 31, v22
	s_and_saveexec_b64 s[46:47], s[42:43]
	s_cbranch_execz .LBB0_1312
	v_lshl_add_u64 v[40:41], v[22:23], 2, s[86:87]
	global_store_dword v[40:41], v32, off
	s_branch .LBB0_1312

; __device__ __forceinline__ float siluf_(float x) { return x * frcp(1.f + __expf(-x)); }
; __device__ __forceinline__ void phase_setup(const Params& p, unsigned char* smem) {
;     ...
;       float* cact = (float*)smem;
;       for (int i = tid; i < 5120; i += 256) {
;         int j = i >> 10, k = i & 1023;
;         float v = (j < 4) ? p.c[j * 1024 + k] : p.c_ctx[k];
;         cact[i] = siluf_(v);
;       }
.LBB0_1360:
	s_and_saveexec_b64 s[56:57], s[46:47]
	v_readlane_b32 s68, v253, 36
	v_readlane_b32 s74, v253, 42
	v_readlane_b32 s75, v253, 43
	v_readlane_b32 s69, v253, 37
	v_readlane_b32 s70, v253, 38
	v_readlane_b32 s71, v253, 39
	v_readlane_b32 s72, v253, 40
	v_readlane_b32 s73, v253, 41
	v_readlane_b32 s76, v253, 44
	v_readlane_b32 s77, v253, 45
	v_readlane_b32 s78, v253, 46
	v_readlane_b32 s79, v253, 47
	v_readlane_b32 s80, v253, 48
	v_readlane_b32 s81, v253, 49
	v_readlane_b32 s82, v253, 50
	v_readlane_b32 s83, v253, 51
	s_cbranch_execz .LBB0_1363
	s_mov_b64 s[60:61], 0x1000
	v_mov_b64_e32 v[14:15], v[12:13]
	v_mov_b32_e32 v1, v25
	v_lshlrev_b32_e32 v18, 2, v0
	v_lshl_add_u64 v[50:51], v[14:15], 0, s[60:61]
	v_lshl_add_u64 v[52:53], v[50:51], 0, s[60:61]
	v_lshl_add_u64 v[54:55], v[52:53], 0, s[60:61]
	global_load_dword v26, v[14:15], off
	global_load_dword v27, v[14:15], off offset:1024
	global_load_dword v28, v[14:15], off offset:2048
	global_load_dword v29, v[14:15], off offset:3072
	global_load_dword v30, v[50:51], off
	global_load_dword v31, v[50:51], off offset:1024
	global_load_dword v32, v[50:51], off offset:2048
	global_load_dword v33, v[50:51], off offset:3072
	global_load_dword v34, v[52:53], off
	global_load_dword v35, v[52:53], off offset:1024
	global_load_dword v36, v[52:53], off offset:2048
	global_load_dword v37, v[52:53], off offset:3072
	global_load_dword v38, v[54:55], off
	global_load_dword v39, v[54:55], off offset:1024
	global_load_dword v40, v[54:55], off offset:2048
	global_load_dword v41, v[54:55], off offset:3072
	global_load_dword v42, v18, s[74:75]
	global_load_dword v43, v18, s[74:75] offset:1024
	global_load_dword v44, v18, s[74:75] offset:2048
	global_load_dword v45, v18, s[74:75] offset:3072
	s_waitcnt vmcnt(0)
	v_mul_f32_e32 v46, 0xbfb8aa3b, v26
	v_mul_f32_e32 v47, 0xbfb8aa3b, v27
	v_mul_f32_e32 v48, 0xbfb8aa3b, v28
	v_mul_f32_e32 v49, 0xbfb8aa3b, v29
	v_exp_f32_e32 v46, v46
	v_exp_f32_e32 v47, v47
	v_exp_f32_e32 v48, v48
	v_exp_f32_e32 v49, v49
	v_add_f32_e32 v46, 1.0, v46
	v_add_f32_e32 v47, 1.0, v47
	v_add_f32_e32 v48, 1.0, v48
	v_add_f32_e32 v49, 1.0, v49
	v_rcp_f32_e32 v46, v46
	v_rcp_f32_e32 v47, v47
	v_rcp_f32_e32 v48, v48
	v_rcp_f32_e32 v49, v49
	v_mul_f32_e32 v26, v26, v46
	v_mul_f32_e32 v27, v27, v47
	v_mul_f32_e32 v28, v28, v48
	v_mul_f32_e32 v29, v29, v49
	ds_write_b32 v1, v26
	ds_write_b32 v1, v27 offset:1024
	ds_write_b32 v1, v28 offset:2048
	ds_write_b32 v1, v29 offset:3072
	v_mul_f32_e32 v46, 0xbfb8aa3b, v30
	v_mul_f32_e32 v47, 0xbfb8aa3b, v31
	v_mul_f32_e32 v48, 0xbfb8aa3b, v32
	v_mul_f32_e32 v49, 0xbfb8aa3b, v33
	v_exp_f32_e32 v46, v46
	v_exp_f32_e32 v47, v47
	v_exp_f32_e32 v48, v48
	v_exp_f32_e32 v49, v49
	v_add_f32_e32 v46, 1.0, v46
	v_add_f32_e32 v47, 1.0, v47
	v_add_f32_e32 v48, 1.0, v48
	v_add_f32_e32 v49, 1.0, v49
	v_rcp_f32_e32 v46, v46
	v_rcp_f32_e32 v47, v47
	v_rcp_f32_e32 v48, v48
	v_rcp_f32_e32 v49, v49
	v_mul_f32_e32 v30, v30, v46
	v_mul_f32_e32 v31, v31, v47
	v_mul_f32_e32 v32, v32, v48
	v_mul_f32_e32 v33, v33, v49
	ds_write_b32 v1, v30 offset:4096
	ds_write_b32 v1, v31 offset:5120
	ds_write_b32 v1, v32 offset:6144
	ds_write_b32 v1, v33 offset:7168
	v_mul_f32_e32 v46, 0xbfb8aa3b, v34
	v_mul_f32_e32 v47, 0xbfb8aa3b, v35
	v_mul_f32_e32 v48, 0xbfb8aa3b, v36
	v_mul_f32_e32 v49, 0xbfb8aa3b, v37
	v_exp_f32_e32 v46, v46
	v_exp_f32_e32 v47, v47
	v_exp_f32_e32 v48, v48
	v_exp_f32_e32 v49, v49
	v_add_f32_e32 v46, 1.0, v46
	v_add_f32_e32 v47, 1.0, v47
	v_add_f32_e32 v48, 1.0, v48
	v_add_f32_e32 v49, 1.0, v49
	v_rcp_f32_e32 v46, v46
	v_rcp_f32_e32 v47, v47
	v_rcp_f32_e32 v48, v48
	v_rcp_f32_e32 v49, v49
	v_mul_f32_e32 v34, v34, v46
	v_mul_f32_e32 v35, v35, v47
	v_mul_f32_e32 v36, v36, v48
	v_mul_f32_e32 v37, v37, v49
	ds_write_b32 v1, v34 offset:8192
	ds_write_b32 v1, v35 offset:9216
	ds_write_b32 v1, v36 offset:10240
	ds_write_b32 v1, v37 offset:11264
	v_mul_f32_e32 v46, 0xbfb8aa3b, v38
	v_mul_f32_e32 v47, 0xbfb8aa3b, v39
	v_mul_f32_e32 v48, 0xbfb8aa3b, v40
	v_mul_f32_e32 v49, 0xbfb8aa3b, v41
	v_exp_f32_e32 v46, v46
	v_exp_f32_e32 v47, v47
	v_exp_f32_e32 v48, v48
	v_exp_f32_e32 v49, v49
	v_add_f32_e32 v46, 1.0, v46
	v_add_f32_e32 v47, 1.0, v47
	v_add_f32_e32 v48, 1.0, v48
	v_add_f32_e32 v49, 1.0, v49
	v_rcp_f32_e32 v46, v46
	v_rcp_f32_e32 v47, v47
	v_rcp_f32_e32 v48, v48
	v_rcp_f32_e32 v49, v49
	v_mul_f32_e32 v38, v38, v46
	v_mul_f32_e32 v39, v39, v47
	v_mul_f32_e32 v40, v40, v48
	v_mul_f32_e32 v41, v41, v49
	ds_write_b32 v1, v38 offset:12288
	ds_write_b32 v1, v39 offset:13312
	ds_write_b32 v1, v40 offset:14336
	ds_write_b32 v1, v41 offset:15360
	v_mul_f32_e32 v46, 0xbfb8aa3b, v42
	v_mul_f32_e32 v47, 0xbfb8aa3b, v43
	v_mul_f32_e32 v48, 0xbfb8aa3b, v44
	v_mul_f32_e32 v49, 0xbfb8aa3b, v45
	v_exp_f32_e32 v46, v46
	v_exp_f32_e32 v47, v47
	v_exp_f32_e32 v48, v48
	v_exp_f32_e32 v49, v49
	v_add_f32_e32 v46, 1.0, v46
	v_add_f32_e32 v47, 1.0, v47
	v_add_f32_e32 v48, 1.0, v48
	v_add_f32_e32 v49, 1.0, v49
	v_rcp_f32_e32 v46, v46
	v_rcp_f32_e32 v47, v47
	v_rcp_f32_e32 v48, v48
	v_rcp_f32_e32 v49, v49
	v_mul_f32_e32 v42, v42, v46
	v_mul_f32_e32 v43, v43, v47
	v_mul_f32_e32 v44, v44, v48
	v_mul_f32_e32 v45, v45, v49
	ds_write_b32 v1, v42 offset:16384
	ds_write_b32 v1, v43 offset:17408
	ds_write_b32 v1, v44 offset:18432
	ds_write_b32 v1, v45 offset:19456
